# stack as before plus the ctx-query D unit epilogue also with batched gain loads and paired 16-byte stores
# speedup vs baseline: 1.0119x; 1.0055x over previous
; #define LAS __attribute__((address_space(3)))
; DI float shx(float v, int m, int lane) { return __builtin_bit_cast(float, __builtin_amdgcn_ds_bpermute((lane ^ m) << 2, __builtin_bit_cast(int, v))); }
; DI void attn_unit_d32(const Ctx& C, const bf16_t* __restrict__ Z, bf16_t* __restrict__ Y, int b, int qsel, int hsel, bool ctxq, float lam, float post_scale, const float* subln, const float mref) {
;     ...
;     float l = lsum; l += shx(l, 32, lane); const float linv = 1.f / l;
;     LAS float* X = (LAS float*)C.lds + (32 * qg + l31) * 132;
;     if (sm == 1) {
; #pragma unroll
;         for (int d = 0; d < 4; ++d)
; #pragma unroll
;             for (int g = 0; g < 4; ++g) { const f32x4 v = {o[d][4 * g] * linv, o[d][4 * g + 1] * linv, o[d][4 * g + 2] * linv, o[d][4 * g + 3] * linv};
;                 *(LAS f32x4*)(X + 32 * d + 8 * g + 4 * hh) = v; }
;     }
;     __syncthreads();
;     if (sm == 0) {
;         f32x4 r[4][4]; float ss = 0.f;
; #pragma unroll
;         for (int d = 0; d < 4; ++d)
; #pragma unroll
;             for (int g = 0; g < 4; ++g) { const f32x4 x2 = *(const LAS f32x4*)(X + 32 * d + 8 * g + 4 * hh);
;                 const f32x4 x1 = {o[d][4 * g] * linv, o[d][4 * g + 1] * linv, o[d][4 * g + 2] * linv, o[d][4 * g + 3] * linv};
;                 r[d][g] = x1 - x2 * lam; ss += (r[d][g][0] * r[d][g][0] + r[d][g][1] * r[d][g][1]) + (r[d][g][2] * r[d][g][2] + r[d][g][3] * r[d][g][3]); }
;         ss += shx(ss, 32, lane);
.LBB0_546:
	s_andn2_b64 vcc, exec, s[6:7]
	s_waitcnt lgkmcnt(0)
	s_barrier
	s_cbranch_vccnz .LBB0_541
	ds_read_b128 v[84:87], v163
	ds_read_b128 v[98:101], v163 offset:32
	v_xor_b32_e32 v96, 0x80000000, v168
	v_pk_mul_f32 v[68:69], v[68:69], v[0:1] op_sel_hi:[1,0]
	v_pk_mul_f32 v[70:71], v[70:71], v[0:1] op_sel_hi:[1,0]
	v_mov_b32_e32 v97, v96
	s_waitcnt lgkmcnt(1)
	v_pk_fma_f32 v[92:93], v[96:97], v[86:87], v[70:71]
	v_pk_fma_f32 v[94:95], v[168:169], v[84:85], v[68:69] neg_lo:[1,0,0] neg_hi:[1,0,0]
	v_pk_mul_f32 v[68:69], v[92:93], v[92:93]
	v_pk_mul_f32 v[70:71], v[94:95], v[94:95]
	v_pk_mul_f32 v[52:53], v[52:53], v[0:1] op_sel_hi:[1,0]
	v_pk_mov_b32 v[84:85], v[70:71], v[68:69] op_sel:[1,0]
	v_mov_b32_e32 v71, v69
	v_pk_add_f32 v[102:103], v[84:85], v[70:71]
	v_pk_mul_f32 v[68:69], v[72:73], v[0:1] op_sel_hi:[1,0]
	v_pk_mul_f32 v[70:71], v[74:75], v[0:1] op_sel_hi:[1,0]
	s_waitcnt lgkmcnt(0)
	v_pk_fma_f32 v[90:91], v[168:169], v[98:99], v[68:69] neg_lo:[1,0,0] neg_hi:[1,0,0]
	v_pk_fma_f32 v[88:89], v[96:97], v[100:101], v[70:71]
	v_pk_mul_f32 v[70:71], v[90:91], v[90:91]
	v_pk_mul_f32 v[68:69], v[88:89], v[88:89]
	v_pk_mul_f32 v[74:75], v[76:77], v[0:1] op_sel_hi:[1,0]
	v_pk_mov_b32 v[72:73], v[70:71], v[68:69] op_sel:[1,0]
	v_mov_b32_e32 v71, v69
	v_pk_add_f32 v[72:73], v[72:73], v[70:71]
	ds_read_b128 v[68:71], v163 offset:64
	v_pk_mul_f32 v[76:77], v[78:79], v[0:1] op_sel_hi:[1,0]
	v_pk_mul_f32 v[54:55], v[54:55], v[0:1] op_sel_hi:[1,0]
	v_pk_mul_f32 v[56:57], v[56:57], v[0:1] op_sel_hi:[1,0]
	v_pk_mul_f32 v[58:59], v[58:59], v[0:1] op_sel_hi:[1,0]
	s_waitcnt lgkmcnt(0)
	v_pk_fma_f32 v[84:85], v[96:97], v[70:71], v[76:77]
	v_pk_fma_f32 v[86:87], v[168:169], v[68:69], v[74:75] neg_lo:[1,0,0] neg_hi:[1,0,0]
	ds_read_b128 v[68:71], v163 offset:96
	v_pk_mul_f32 v[74:75], v[80:81], v[0:1] op_sel_hi:[1,0]
	v_pk_mul_f32 v[76:77], v[82:83], v[0:1] op_sel_hi:[1,0]
	v_pk_mul_f32 v[36:37], v[36:37], v[0:1] op_sel_hi:[1,0]
	v_pk_mul_f32 v[38:39], v[38:39], v[0:1] op_sel_hi:[1,0]
	s_waitcnt lgkmcnt(0)
	v_pk_fma_f32 v[78:79], v[168:169], v[68:69], v[74:75] neg_lo:[1,0,0] neg_hi:[1,0,0]
	v_pk_fma_f32 v[76:77], v[96:97], v[70:71], v[76:77]
	v_mul_f32_e32 v70, v78, v78
	v_pk_add_f32 v[68:69], v[102:103], v[102:103] op_sel:[0,1] op_sel_hi:[1,0]
	v_mul_f32_e32 v74, v79, v79
	v_mov_b32_e32 v69, v70
	v_pk_add_f32 v[70:71], v[72:73], v[72:73] op_sel:[0,1] op_sel_hi:[1,0]
	v_mul_f32_e32 v72, v85, v85
	v_mov_b32_e32 v71, v74
	v_pk_add_f32 v[68:69], v[68:69], v[70:71]
	v_mul_f32_e32 v70, v87, v87
	v_mul_f32_e32 v75, v76, v76
	v_mul_f32_e32 v80, v77, v77
	v_pk_fma_f32 v[70:71], v[86:87], v[86:87], v[70:71] op_sel_hi:[1,1,0]
	v_pk_fma_f32 v[72:73], v[84:85], v[84:85], v[72:73] op_sel_hi:[1,1,0]
	v_mov_b32_e32 v71, v75
	v_mov_b32_e32 v73, v80
	v_pk_add_f32 v[70:71], v[70:71], v[72:73]
	v_pk_mul_f32 v[40:41], v[40:41], v[0:1] op_sel_hi:[1,0]
	v_pk_add_f32 v[80:81], v[68:69], v[70:71]
	ds_read_b128 v[70:73], v163 offset:128
	v_pk_mul_f32 v[42:43], v[42:43], v[0:1] op_sel_hi:[1,0]
	v_pk_mul_f32 v[24:25], v[24:25], v[0:1] op_sel_hi:[1,0]
	v_pk_mul_f32 v[26:27], v[26:27], v[0:1] op_sel_hi:[1,0]
	v_pk_mul_f32 v[28:29], v[28:29], v[0:1] op_sel_hi:[1,0]
	s_waitcnt lgkmcnt(0)
	v_pk_fma_f32 v[68:69], v[96:97], v[72:73], v[54:55]
	v_pk_fma_f32 v[70:71], v[168:169], v[70:71], v[52:53] neg_lo:[1,0,0] neg_hi:[1,0,0]
	v_pk_mul_f32 v[52:53], v[68:69], v[68:69]
	v_pk_mul_f32 v[54:55], v[70:71], v[70:71]
	v_pk_mul_f32 v[30:31], v[30:31], v[0:1] op_sel_hi:[1,0]
	v_pk_mov_b32 v[72:73], v[54:55], v[52:53] op_sel:[1,0]
	v_mov_b32_e32 v55, v53
	v_pk_add_f32 v[82:83], v[72:73], v[54:55]
	ds_read_b128 v[52:55], v163 offset:160
	v_pk_mul_f32 v[32:33], v[32:33], v[0:1] op_sel_hi:[1,0]
	v_mov_b32_e32 v153, v1
	s_lshl_b32 s36, s18, 1
	s_waitcnt lgkmcnt(0)
	v_pk_fma_f32 v[72:73], v[96:97], v[54:55], v[58:59]
	v_pk_fma_f32 v[74:75], v[168:169], v[52:53], v[56:57] neg_lo:[1,0,0] neg_hi:[1,0,0]
	ds_read_b128 v[54:57], v163 offset:192
	v_pk_mul_f32 v[58:59], v[60:61], v[0:1] op_sel_hi:[1,0]
	v_pk_mul_f32 v[52:53], v[62:63], v[0:1] op_sel_hi:[1,0]
	s_waitcnt lgkmcnt(0)
	v_pk_fma_f32 v[54:55], v[168:169], v[54:55], v[58:59] neg_lo:[1,0,0] neg_hi:[1,0,0]
	v_pk_fma_f32 v[52:53], v[96:97], v[56:57], v[52:53]
	v_mul_f32_e32 v58, v54, v54
	v_pk_add_f32 v[56:57], v[80:81], v[80:81] op_sel:[0,1] op_sel_hi:[1,0]
	v_mul_f32_e32 v60, v55, v55
	v_mov_b32_e32 v57, v58
	v_pk_add_f32 v[58:59], v[82:83], v[82:83] op_sel:[0,1] op_sel_hi:[1,0]
	v_mul_f32_e32 v61, v52, v52
	v_mov_b32_e32 v59, v60
	v_pk_add_f32 v[56:57], v[56:57], v[58:59]
	v_mul_f32_e32 v58, v75, v75
	v_pk_fma_f32 v[58:59], v[74:75], v[74:75], v[58:59] op_sel_hi:[1,1,0]
	v_mul_f32_e32 v60, v73, v73
	v_mul_f32_e32 v62, v53, v53
	v_mov_b32_e32 v59, v61
	v_pk_fma_f32 v[60:61], v[72:73], v[72:73], v[60:61] op_sel_hi:[1,1,0]
	s_nop 0
	v_mov_b32_e32 v61, v62
	v_pk_add_f32 v[58:59], v[58:59], v[60:61]
	v_pk_mul_f32 v[60:61], v[64:65], v[0:1] op_sel_hi:[1,0]
	v_pk_add_f32 v[80:81], v[56:57], v[58:59]
	ds_read_b128 v[56:59], v163 offset:224
	v_pk_mul_f32 v[62:63], v[66:67], v[0:1] op_sel_hi:[1,0]
	s_waitcnt lgkmcnt(0)
	v_pk_fma_f32 v[66:67], v[168:169], v[56:57], v[60:61] neg_lo:[1,0,0] neg_hi:[1,0,0]
	v_pk_fma_f32 v[64:65], v[96:97], v[58:59], v[62:63]
	v_pk_mul_f32 v[58:59], v[66:67], v[66:67]
	v_pk_mul_f32 v[56:57], v[64:65], v[64:65]
	s_nop 0
	v_pk_mov_b32 v[60:61], v[58:59], v[56:57] op_sel:[1,0]
	v_mov_b32_e32 v59, v57
	v_pk_add_f32 v[82:83], v[60:61], v[58:59]
	ds_read_b128 v[56:59], v163 offset:256
	s_waitcnt lgkmcnt(0)
	v_pk_fma_f32 v[60:61], v[96:97], v[58:59], v[38:39]
	v_pk_fma_f32 v[62:63], v[168:169], v[56:57], v[36:37] neg_lo:[1,0,0] neg_hi:[1,0,0]
	ds_read_b128 v[36:39], v163 offset:288
	s_waitcnt lgkmcnt(0)
; #define LAS __attribute__((address_space(3)))
; DI float shx(float v, int m, int lane) { return __builtin_bit_cast(float, __builtin_amdgcn_ds_bpermute((lane ^ m) << 2, __builtin_bit_cast(int, v))); }
; DI void attn_unit_d32(const Ctx& C, const bf16_t* __restrict__ Z, bf16_t* __restrict__ Y, int b, int qsel, int hsel, bool ctxq, float lam, float post_scale, const float* subln, const float mref) {
;     ...
;         f32x4 r[4][4]; float ss = 0.f;
; #pragma unroll
;         for (int d = 0; d < 4; ++d)
; #pragma unroll
;             for (int g = 0; g < 4; ++g) { const f32x4 x2 = *(const LAS f32x4*)(X + 32 * d + 8 * g + 4 * hh);
;                 const f32x4 x1 = {o[d][4 * g] * linv, o[d][4 * g + 1] * linv, o[d][4 * g + 2] * linv, o[d][4 * g + 3] * linv};
;                 r[d][g] = x1 - x2 * lam; ss += (r[d][g][0] * r[d][g][0] + r[d][g][1] * r[d][g][1]) + (r[d][g][2] * r[d][g][2] + r[d][g][3] * r[d][g][3]); }
;         ss += shx(ss, 32, lane);
	v_pk_fma_f32 v[58:59], v[168:169], v[36:37], v[40:41] neg_lo:[1,0,0] neg_hi:[1,0,0]
	v_pk_fma_f32 v[56:57], v[96:97], v[38:39], v[42:43]
	v_mul_f32_e32 v38, v58, v58
	v_pk_add_f32 v[36:37], v[80:81], v[80:81] op_sel:[0,1] op_sel_hi:[1,0]
	v_mul_f32_e32 v40, v59, v59
	v_mov_b32_e32 v37, v38
	v_pk_add_f32 v[38:39], v[82:83], v[82:83] op_sel:[0,1] op_sel_hi:[1,0]
	v_mul_f32_e32 v41, v56, v56
	v_mov_b32_e32 v39, v40
	v_pk_add_f32 v[36:37], v[36:37], v[38:39]
	v_mul_f32_e32 v38, v63, v63
	v_pk_fma_f32 v[38:39], v[62:63], v[62:63], v[38:39] op_sel_hi:[1,1,0]
	v_mul_f32_e32 v40, v61, v61
	v_mul_f32_e32 v42, v57, v57
	v_mov_b32_e32 v39, v41
	v_pk_fma_f32 v[40:41], v[60:61], v[60:61], v[40:41] op_sel_hi:[1,1,0]
	s_nop 0
	v_mov_b32_e32 v41, v42
	v_pk_add_f32 v[38:39], v[38:39], v[40:41]
	v_pk_mul_f32 v[42:43], v[44:45], v[0:1] op_sel_hi:[1,0]
	v_pk_add_f32 v[80:81], v[36:37], v[38:39]
	ds_read_b128 v[36:39], v163 offset:320
	v_pk_mul_f32 v[40:41], v[46:47], v[0:1] op_sel_hi:[1,0]
	s_waitcnt lgkmcnt(0)
	v_pk_fma_f32 v[42:43], v[168:169], v[36:37], v[42:43] neg_lo:[1,0,0] neg_hi:[1,0,0]
	v_pk_fma_f32 v[40:41], v[96:97], v[38:39], v[40:41]
	v_pk_mul_f32 v[38:39], v[42:43], v[42:43]
	v_pk_mul_f32 v[36:37], v[40:41], v[40:41]
	s_nop 0
	v_pk_mov_b32 v[44:45], v[38:39], v[36:37] op_sel:[1,0]
	v_mov_b32_e32 v39, v37
	v_pk_add_f32 v[82:83], v[44:45], v[38:39]
	ds_read_b128 v[44:47], v163 offset:352
	v_pk_mul_f32 v[38:39], v[48:49], v[0:1] op_sel_hi:[1,0]
	v_pk_mul_f32 v[36:37], v[50:51], v[0:1] op_sel_hi:[1,0]
	v_pk_mul_f32 v[48:49], v[20:21], v[0:1] op_sel_hi:[1,0]
	v_pk_mul_f32 v[20:21], v[22:23], v[0:1] op_sel_hi:[1,0]
	s_waitcnt lgkmcnt(0)
	v_pk_fma_f32 v[36:37], v[96:97], v[46:47], v[36:37]
	v_pk_fma_f32 v[38:39], v[168:169], v[44:45], v[38:39] neg_lo:[1,0,0] neg_hi:[1,0,0]
	ds_read_b128 v[44:47], v163 offset:384
	s_waitcnt lgkmcnt(0)
	v_pk_fma_f32 v[22:23], v[168:169], v[44:45], v[48:49] neg_lo:[1,0,0] neg_hi:[1,0,0]
	v_pk_fma_f32 v[20:21], v[96:97], v[46:47], v[20:21]
	v_mul_f32_e32 v46, v22, v22
	v_pk_add_f32 v[44:45], v[80:81], v[80:81] op_sel:[0,1] op_sel_hi:[1,0]
	v_mul_f32_e32 v48, v23, v23
	v_mov_b32_e32 v45, v46
	v_pk_add_f32 v[46:47], v[82:83], v[82:83] op_sel:[0,1] op_sel_hi:[1,0]
	v_mul_f32_e32 v49, v20, v20
	v_mov_b32_e32 v47, v48
	v_pk_add_f32 v[44:45], v[44:45], v[46:47]
	v_mul_f32_e32 v46, v39, v39
	v_pk_fma_f32 v[46:47], v[38:39], v[38:39], v[46:47] op_sel_hi:[1,1,0]
	v_mul_f32_e32 v48, v37, v37
	v_mul_f32_e32 v50, v21, v21
	v_mov_b32_e32 v47, v49
	v_pk_fma_f32 v[48:49], v[36:37], v[36:37], v[48:49] op_sel_hi:[1,1,0]
	s_nop 0
	v_mov_b32_e32 v49, v50
	v_pk_add_f32 v[46:47], v[46:47], v[48:49]
	s_nop 0
	v_pk_add_f32 v[50:51], v[44:45], v[46:47]
	ds_read_b128 v[44:47], v163 offset:416
	s_waitcnt lgkmcnt(0)
	v_pk_fma_f32 v[46:47], v[96:97], v[46:47], v[26:27]
	v_pk_fma_f32 v[48:49], v[168:169], v[44:45], v[24:25] neg_lo:[1,0,0] neg_hi:[1,0,0]
	v_pk_mul_f32 v[24:25], v[46:47], v[46:47]
	v_pk_mul_f32 v[26:27], v[48:49], v[48:49]
	s_nop 0
	v_pk_mov_b32 v[44:45], v[26:27], v[24:25] op_sel:[1,0]
	v_mov_b32_e32 v27, v25
	v_pk_add_f32 v[80:81], v[44:45], v[26:27]
	ds_read_b128 v[24:27], v163 offset:448
	s_waitcnt lgkmcnt(0)
	v_pk_fma_f32 v[30:31], v[96:97], v[26:27], v[30:31]
	v_pk_fma_f32 v[44:45], v[168:169], v[24:25], v[28:29] neg_lo:[1,0,0] neg_hi:[1,0,0]
	ds_read_b128 v[26:29], v163 offset:480
	v_pk_mul_f32 v[24:25], v[34:35], v[0:1] op_sel_hi:[1,0]
	s_waitcnt lgkmcnt(0)
	v_pk_fma_f32 v[26:27], v[168:169], v[26:27], v[32:33] neg_lo:[1,0,0] neg_hi:[1,0,0]
	v_pk_fma_f32 v[24:25], v[96:97], v[28:29], v[24:25]
	v_mul_f32_e32 v0, v26, v26
	v_mul_f32_e32 v34, v27, v27
	v_pk_add_f32 v[28:29], v[50:51], v[50:51] op_sel:[0,1] op_sel_hi:[1,0]
	v_pk_add_f32 v[32:33], v[80:81], v[80:81] op_sel:[0,1] op_sel_hi:[1,0]
	v_mov_b32_e32 v29, v0
	v_mov_b32_e32 v33, v34
	v_mul_f32_e32 v0, v45, v45
	v_mul_f32_e32 v35, v24, v24
	v_pk_add_f32 v[28:29], v[28:29], v[32:33]
	v_pk_fma_f32 v[32:33], v[44:45], v[44:45], v[0:1] op_sel_hi:[1,1,0]
	v_mul_f32_e32 v0, v31, v31
	v_mul_f32_e32 v82, v25, v25
	v_mov_b32_e32 v33, v35
	v_pk_fma_f32 v[34:35], v[30:31], v[30:31], v[0:1] op_sel_hi:[1,1,0]
	s_nop 0
	v_mov_b32_e32 v35, v82
	v_pk_add_f32 v[32:33], v[32:33], v[34:35]
	s_nop 0
	v_pk_add_f32 v[28:29], v[28:29], v[32:33]
	s_nop 0
	v_add_f32_e32 v0, v28, v29
	ds_bpermute_b32 v28, v158, v0
	s_waitcnt lgkmcnt(0)
; #define GAS __attribute__((address_space(1)))
; DI unsigned pk2(float lo, float hi) { f32x2 v = {lo, hi}; bf16x2_t b = __builtin_convertvector(v, bf16x2_t); return __builtin_bit_cast(unsigned, b); }
; DI float shx(float v, int m, int lane) { return __builtin_bit_cast(float, __builtin_amdgcn_ds_bpermute((lane ^ m) << 2, __builtin_bit_cast(int, v))); }
; DI void attn_unit_d32(const Ctx& C, const bf16_t* __restrict__ Z, bf16_t* __restrict__ Y, int b, int qsel, int hsel, bool ctxq, float lam, float post_scale, const float* subln, const float mref) {
;     ...
;         ss += shx(ss, 32, lane);
;         const float rs = post_scale / sqrtf(ss * (1.f / 128.f) + EPS);
;         bf16_t* yp = Y + (size_t)qrow * DM + ycol;
; #pragma unroll
;         for (int d = 0; d < 4; ++d)
; #pragma unroll
;             for (int g = 0; g < 4; ++g) { const int dv = 32 * d + 8 * g + 4 * hh; const f32x4 gn = *(const GAS f32x4*)(subln + dv); const f32x4 v = r[d][g] * rs * gn;
;                 u32x2 wv; wv.x = pk2(v[0], v[1]); wv.y = pk2(v[2], v[3]); *(GAS u32x2*)(yp + dv) = wv; }
	v_add_f32_e32 v0, v0, v28
	v_fmamk_f32 v0, v0, 0x3c000000, v227
	v_cmp_gt_f32_e32 vcc, s67, v0
	v_mul_f32_e32 v28, 0x4f800000, v0
	s_nop 0
	v_cndmask_b32_e32 v0, v0, v28, vcc
	v_sqrt_f32_e32 v28, v0
	s_nop 0
	v_add_u32_e32 v29, -1, v28
	v_fma_f32 v32, -v29, v28, v0
	v_cmp_ge_f32_e64 s[0:1], 0, v32
	v_add_u32_e32 v32, 1, v28
	s_nop 0
	v_cndmask_b32_e64 v29, v28, v29, s[0:1]
	v_fma_f32 v28, -v32, v28, v0
	v_cmp_lt_f32_e64 s[0:1], 0, v28
	s_nop 1
	v_cndmask_b32_e64 v28, v29, v32, s[0:1]
	v_mul_f32_e32 v29, 0x37800000, v28
	v_cndmask_b32_e32 v28, v28, v29, vcc
	v_cmp_class_f32_e32 vcc, v0, v228
	s_nop 1
	v_cndmask_b32_e32 v0, v28, v0, vcc
	v_div_scale_f32 v28, s[0:1], v0, v0, v176
	v_rcp_f32_e32 v29, v28
	s_nop 0
	v_fma_f32 v32, -v28, v29, 1.0
	v_fmac_f32_e32 v29, v32, v29
	v_div_scale_f32 v32, vcc, v176, v0, v176
	v_mul_f32_e32 v33, v32, v29
	v_fma_f32 v34, -v28, v33, v32
	v_fmac_f32_e32 v33, v34, v29
	v_fma_f32 v28, -v28, v33, v32
	v_div_fmas_f32 v28, v28, v29, v33
	global_load_dwordx4 v[130:133], v[150:151], off
	global_load_dwordx4 v[138:141], v[150:151], off offset:32
	global_load_dwordx4 v[142:145], v[150:151], off offset:64
	global_load_dwordx4 v[164:167], v[150:151], off offset:96
	global_load_dwordx4 v[170:173], v[150:151], off offset:128
	global_load_dwordx4 v[178:181], v[150:151], off offset:160
	global_load_dwordx4 v[182:185], v[150:151], off offset:192
	global_load_dwordx4 v[186:189], v[150:151], off offset:224
	global_load_dwordx4 v[190:193], v[150:151], off offset:256
	global_load_dwordx4 v[202:205], v[150:151], off offset:288
	global_load_dwordx4 v[210:213], v[150:151], off offset:320
	global_load_dwordx4 v[214:217], v[150:151], off offset:352
	global_load_dwordx4 v[218:221], v[150:151], off offset:384
	global_load_dwordx4 v[222:225], v[150:151], off offset:416
	global_load_dwordx4 v[240:243], v[150:151], off offset:448
	global_load_dwordx4 v[244:247], v[150:151], off offset:480
	v_div_fixup_f32 v0, v28, v0, v176
	v_lshlrev_b64 v[28:29], 12, v[152:153]
	v_lshl_add_u64 v[28:29], s[10:11], 0, v[28:29]
	v_pk_mul_f32 v[50:51], v[94:95], v[0:1] op_sel_hi:[1,0]
	v_pk_mul_f32 v[80:81], v[92:93], v[0:1] op_sel_hi:[1,0]
	v_lshl_add_u64 v[28:29], v[28:29], 0, s[36:37]
	v_lshl_add_u64 v[28:29], v[148:149], 1, v[28:29]
	v_mbcnt_lo_u32_b32 v146, -1, 0
	v_mbcnt_hi_u32_b32 v146, -1, v146
	v_mov_b32_e32 v147, 0
	v_and_b32_e32 v146, 32, v146
	v_lshrrev_b32_e32 v146, 2, v146
	v_lshl_add_u64 v[134:135], v[146:147], 0, v[28:29]
	v_pk_mul_f32 v[76:77], v[76:77], v[0:1] op_sel_hi:[1,0]
	v_pk_mul_f32 v[68:69], v[68:69], v[0:1] op_sel_hi:[1,0]
	v_pk_mul_f32 v[52:53], v[52:53], v[0:1] op_sel_hi:[1,0]
	v_pk_mul_f32 v[42:43], v[42:43], v[0:1] op_sel_hi:[1,0]
	v_pk_mul_f32 v[40:41], v[40:41], v[0:1] op_sel_hi:[1,0]
	v_pk_mul_f32 v[38:39], v[38:39], v[0:1] op_sel_hi:[1,0]
	v_pk_mul_f32 v[36:37], v[36:37], v[0:1] op_sel_hi:[1,0]
	v_pk_mul_f32 v[22:23], v[22:23], v[0:1] op_sel_hi:[1,0]
	v_pk_mul_f32 v[20:21], v[20:21], v[0:1] op_sel_hi:[1,0]
	v_pk_mul_f32 v[30:31], v[30:31], v[0:1] op_sel_hi:[1,0]
	v_pk_mul_f32 v[26:27], v[26:27], v[0:1] op_sel_hi:[1,0]
	v_pk_mul_f32 v[24:25], v[24:25], v[0:1] op_sel_hi:[1,0]
	s_waitcnt vmcnt(0)
; #define GAS __attribute__((address_space(1)))
; DI unsigned pk2(float lo, float hi) { f32x2 v = {lo, hi}; bf16x2_t b = __builtin_convertvector(v, bf16x2_t); return __builtin_bit_cast(unsigned, b); }
; DI void attn_unit_d32(const Ctx& C, const bf16_t* __restrict__ Z, bf16_t* __restrict__ Y, int b, int qsel, int hsel, bool ctxq, float lam, float post_scale, const float* subln, const float mref) {
;     ...
; #pragma unroll
;         for (int d = 0; d < 4; ++d)
; #pragma unroll
;             for (int g = 0; g < 4; ++g) { const int dv = 32 * d + 8 * g + 4 * hh; const f32x4 gn = *(const GAS f32x4*)(subln + dv); const f32x4 v = r[d][g] * rs * gn;
;                 u32x2 wv; wv.x = pk2(v[0], v[1]); wv.y = pk2(v[2], v[3]); *(GAS u32x2*)(yp + dv) = wv; }
	v_pk_mul_f32 v[34:35], v[132:133], v[80:81]
	v_pk_mul_f32 v[32:33], v[130:131], v[50:51]
	v_pk_mul_f32 v[50:51], v[90:91], v[0:1] op_sel_hi:[1,0]
	v_cvt_pk_bf16_f32 v130, v32, v33
	v_cvt_pk_bf16_f32 v131, v34, v35
	v_pk_mul_f32 v[80:81], v[88:89], v[0:1] op_sel_hi:[1,0]
	v_pk_mul_f32 v[32:33], v[138:139], v[50:51]
	v_pk_mul_f32 v[34:35], v[140:141], v[80:81]
	v_cvt_pk_bf16_f32 v132, v32, v33
	v_cvt_pk_bf16_f32 v133, v34, v35
	s_nop 1
	v_permlane32_swap_b32 v130, v132
	v_permlane32_swap_b32 v131, v133
	global_store_dwordx4 v[134:135], v[130:133], off offset:3072
	v_pk_mul_f32 v[50:51], v[86:87], v[0:1] op_sel_hi:[1,0]
	v_pk_mul_f32 v[80:81], v[84:85], v[0:1] op_sel_hi:[1,0]
	v_pk_mul_f32 v[32:33], v[142:143], v[50:51]
	v_pk_mul_f32 v[34:35], v[144:145], v[80:81]
	v_cvt_pk_bf16_f32 v142, v32, v33
	v_cvt_pk_bf16_f32 v143, v34, v35
	v_pk_mul_f32 v[50:51], v[78:79], v[0:1] op_sel_hi:[1,0]
	v_pk_mul_f32 v[34:35], v[166:167], v[76:77]
	v_pk_mul_f32 v[32:33], v[164:165], v[50:51]
	v_pk_mul_f32 v[50:51], v[70:71], v[0:1] op_sel_hi:[1,0]
	v_cvt_pk_bf16_f32 v144, v32, v33
	v_cvt_pk_bf16_f32 v145, v34, v35
	s_nop 1
	v_permlane32_swap_b32 v142, v144
	v_permlane32_swap_b32 v143, v145
	global_store_dwordx4 v[134:135], v[142:145], off offset:3104
	v_pk_mul_f32 v[34:35], v[172:173], v[68:69]
	v_pk_mul_f32 v[32:33], v[170:171], v[50:51]
	v_pk_mul_f32 v[50:51], v[74:75], v[0:1] op_sel_hi:[1,0]
	v_cvt_pk_bf16_f32 v170, v32, v33
	v_cvt_pk_bf16_f32 v171, v34, v35
	v_pk_mul_f32 v[68:69], v[72:73], v[0:1] op_sel_hi:[1,0]
	v_pk_mul_f32 v[32:33], v[178:179], v[50:51]
	v_pk_mul_f32 v[34:35], v[180:181], v[68:69]
	v_cvt_pk_bf16_f32 v172, v32, v33
	v_cvt_pk_bf16_f32 v173, v34, v35
	s_nop 1
	v_permlane32_swap_b32 v170, v172
	v_permlane32_swap_b32 v171, v173
	global_store_dwordx4 v[134:135], v[170:173], off offset:3136
	v_pk_mul_f32 v[50:51], v[54:55], v[0:1] op_sel_hi:[1,0]
	v_pk_mul_f32 v[34:35], v[184:185], v[52:53]
	v_pk_mul_f32 v[32:33], v[182:183], v[50:51]
	v_pk_mul_f32 v[50:51], v[66:67], v[0:1] op_sel_hi:[1,0]
	v_cvt_pk_bf16_f32 v182, v32, v33
	v_cvt_pk_bf16_f32 v183, v34, v35
	v_pk_mul_f32 v[52:53], v[64:65], v[0:1] op_sel_hi:[1,0]
	v_pk_mul_f32 v[32:33], v[50:51], v[186:187]
	v_pk_mul_f32 v[34:35], v[52:53], v[188:189]
	v_cvt_pk_bf16_f32 v184, v32, v33
	v_cvt_pk_bf16_f32 v185, v34, v35
	s_nop 1
	v_permlane32_swap_b32 v182, v184
	v_permlane32_swap_b32 v183, v185
	global_store_dwordx4 v[134:135], v[182:185], off offset:3168
	v_pk_mul_f32 v[50:51], v[62:63], v[0:1] op_sel_hi:[1,0]
	v_pk_mul_f32 v[52:53], v[60:61], v[0:1] op_sel_hi:[1,0]
	v_pk_mul_f32 v[32:33], v[50:51], v[190:191]
	v_pk_mul_f32 v[34:35], v[52:53], v[192:193]
	v_cvt_pk_bf16_f32 v190, v32, v33
	v_cvt_pk_bf16_f32 v191, v34, v35
	v_pk_mul_f32 v[50:51], v[58:59], v[0:1] op_sel_hi:[1,0]
	v_pk_mul_f32 v[52:53], v[56:57], v[0:1] op_sel_hi:[1,0]
	v_pk_mul_f32 v[32:33], v[50:51], v[202:203]
	v_pk_mul_f32 v[34:35], v[52:53], v[204:205]
	v_cvt_pk_bf16_f32 v192, v32, v33
	v_cvt_pk_bf16_f32 v193, v34, v35
	s_nop 1
	v_permlane32_swap_b32 v190, v192
	v_permlane32_swap_b32 v191, v193
	global_store_dwordx4 v[134:135], v[190:193], off offset:3200
	v_pk_mul_f32 v[34:35], v[40:41], v[212:213]
	v_pk_mul_f32 v[32:33], v[42:43], v[210:211]
	s_nop 0
	v_cvt_pk_bf16_f32 v210, v32, v33
	v_cvt_pk_bf16_f32 v211, v34, v35
	v_pk_mul_f32 v[34:35], v[36:37], v[216:217]
	v_pk_mul_f32 v[32:33], v[38:39], v[214:215]
	s_nop 0
	v_cvt_pk_bf16_f32 v212, v32, v33
	v_cvt_pk_bf16_f32 v213, v34, v35
	s_nop 1
	v_permlane32_swap_b32 v210, v212
	v_permlane32_swap_b32 v211, v213
	global_store_dwordx4 v[134:135], v[210:213], off offset:3232
	v_pk_mul_f32 v[20:21], v[20:21], v[220:221]
	v_pk_mul_f32 v[22:23], v[22:23], v[218:219]
	v_pk_mul_f32 v[32:33], v[48:49], v[0:1] op_sel_hi:[1,0]
	v_cvt_pk_bf16_f32 v218, v22, v23
	v_cvt_pk_bf16_f32 v219, v20, v21
	v_pk_mul_f32 v[34:35], v[46:47], v[0:1] op_sel_hi:[1,0]
	v_pk_mul_f32 v[20:21], v[32:33], v[222:223]
	v_pk_mul_f32 v[22:23], v[34:35], v[224:225]
	v_cvt_pk_bf16_f32 v220, v20, v21
	v_cvt_pk_bf16_f32 v221, v22, v23
	s_nop 1
	v_permlane32_swap_b32 v218, v220
	v_permlane32_swap_b32 v219, v221
	global_store_dwordx4 v[134:135], v[218:221], off offset:3264
	v_pk_mul_f32 v[32:33], v[44:45], v[0:1] op_sel_hi:[1,0]
	v_pk_mul_f32 v[22:23], v[30:31], v[242:243]
	v_pk_mul_f32 v[20:21], v[32:33], v[240:241]
	s_nop 0
	v_cvt_pk_bf16_f32 v240, v20, v21
	v_cvt_pk_bf16_f32 v241, v22, v23
	v_pk_mul_f32 v[22:23], v[24:25], v[246:247]
	v_pk_mul_f32 v[20:21], v[26:27], v[244:245]
	s_nop 0
	v_cvt_pk_bf16_f32 v242, v20, v21
	v_cvt_pk_bf16_f32 v243, v22, v23
	s_nop 1
	v_permlane32_swap_b32 v240, v242
	v_permlane32_swap_b32 v241, v243
	global_store_dwordx4 v[134:135], v[240:243], off offset:3296
	s_branch .LBB0_541
